# WDN (P8 B operand) stored in lane-linear 16x32 block layout with perm32 folded into the transpose store; P8 B-side LDS-DMA/ds_read addressing adapted
# baseline (speedup 1.0000x reference)
; #define LAS __attribute__((address_space(3)))
; __device__ __forceinline__ unsigned cvt_pk_bf16(float lo, float hi) { unsigned r; asm volatile("v_cvt_pk_bf16_f32 %0, %1, %2" : "=v"(r) : "v"(lo), "v"(hi)); return r; }
; __device__ __forceinline__ void transpose_item(const float* W, int K, int N, bf16_t* WT, int k0, int n0, int drow0, const float* gs, LAS float* scr, int lane) {
;     ...
;     for (int i = 0; i < 32; ++i) scr[(2 * i + (lane >> 5)) * 33 + (lane & 31)] = tv[i];
;     asm volatile("s_waitcnt lgkmcnt(0)" ::: "memory");
;     const int c = lane & 7;
; #pragma unroll
;     for (int j = 0; j < 4; ++j) { const int n = (lane >> 3) + 8 * j; const LAS float* s = scr + (8 * c) * 33 + n;
;         u32x4 o; o.x = cvt_pk_bf16(s[0 * 33], s[1 * 33]); o.y = cvt_pk_bf16(s[2 * 33], s[3 * 33]); o.z = cvt_pk_bf16(s[4 * 33], s[5 * 33]); o.w = cvt_pk_bf16(s[6 * 33], s[7 * 33]);
;         *(u32x4*)(WT + (size_t)(drow0 + n) * K + k0 + 8 * c) = o; }
; __global__ void __launch_bounds__(512, 2) fwd(Args a) {
;     ...
;                 else { r -= I_GLU + I_OUT + I_UP; W = a.in[I_WDN]; WT = WDN; K_ = DFF; N_ = D; }
;                 const int nbk = N_ / 32, kb = r / nbk, nb = r % nbk;
;                 transpose_item(W, K_, N_, WT, 64 * kb, 32 * nb, 32 * nb, gs, scr, lane); }
.LBB0_247:
	s_waitcnt vmcnt(30)
	ds_write2_b32 v44, v4, v5 offset1:66
	s_waitcnt vmcnt(28)
	ds_write2_b32 v44, v8, v9 offset0:132 offset1:198
	v_add_u32_e32 v4, 0x400, v44
	s_waitcnt vmcnt(26)
	ds_write2_b32 v4, v6, v7 offset0:8 offset1:74
	s_waitcnt vmcnt(24)
	ds_write2_b32 v4, v10, v11 offset0:140 offset1:206
	v_add_u32_e32 v4, 0x800, v44
	s_waitcnt vmcnt(22)
	ds_write2_b32 v4, v12, v13 offset0:16 offset1:82
	s_waitcnt vmcnt(20)
	ds_write2_b32 v4, v16, v17 offset0:148 offset1:214
	v_add_u32_e32 v4, 0xc00, v44
	s_waitcnt vmcnt(18)
	ds_write2_b32 v4, v14, v15 offset0:24 offset1:90
	s_waitcnt vmcnt(16)
	ds_write2_b32 v4, v18, v19 offset0:156 offset1:222
	v_add_u32_e32 v4, 0x1000, v44
	s_waitcnt vmcnt(14)
	ds_write2_b32 v4, v20, v21 offset0:32 offset1:98
	s_waitcnt vmcnt(12)
	ds_write2_b32 v4, v24, v25 offset0:164 offset1:230
	v_add_u32_e32 v4, 0x1400, v44
	s_waitcnt vmcnt(10)
	ds_write2_b32 v4, v22, v23 offset0:40 offset1:106
	s_waitcnt vmcnt(8)
	ds_write2_b32 v4, v26, v27 offset0:172 offset1:238
	v_add_u32_e32 v4, 0x1800, v44
	s_ashr_i32 s71, s70, 31
	s_waitcnt vmcnt(6)
	ds_write2_b32 v4, v30, v31 offset0:48 offset1:114
	s_waitcnt vmcnt(4)
	ds_write2_b32 v4, v36, v37 offset0:180 offset1:246
	v_add_u32_e32 v4, 0x1c00, v44
	s_lshl_b64 s[34:35], s[70:71], 1
	s_waitcnt vmcnt(2)
	ds_write2_b32 v4, v34, v35 offset0:56 offset1:122
	s_waitcnt vmcnt(0)
	ds_write2_b32 v4, v32, v33 offset0:188 offset1:254
	s_add_u32 s34, s62, s34
	s_waitcnt lgkmcnt(0)
	s_addc_u32 s35, s63, s35
	s_lshl_b32 s98, s10, 14
	s_lshl_b32 s99, s70, 5
	s_add_u32 s98, s98, s99
	s_add_u32 s98, s62, s98
	s_addc_u32 s99, s63, 0
	s_cmp_eq_u32 s8, 0x2000
	s_cselect_b32 s100, 1, 0
	v_bfe_u32 v122, v39, 2, 1
	v_lshlrev_b32_e32 v122, 18, v122
	v_and_b32_e32 v123, 3, v39
	v_lshl_or_b32 v122, v123, 4, v122
	v_bfe_u32 v123, v0, 6, 1
	v_lshl_or_b32 v122, v123, 10, v122
	v_bfe_u32 v123, v0, 4, 2
	v_lshl_or_b32 v122, v123, 8, v122
	v_mov_b32_e32 v123, 0
	v_lshl_add_u64 v[120:121], s[98:99], 0, v[122:123]
	v_or_b32_e32 v12, s10, v39
	ds_read2_b32 v[4:5], v40 offset1:33
	v_lshl_add_u64 v[10:11], s[34:35], 0, v[0:1]
	v_mul_lo_u32 v14, s9, v12
	s_mul_i32 s5, s8, s11
	v_mad_u64_u32 v[12:13], s[34:35], s8, v12, 0
	s_waitcnt lgkmcnt(0)
	v_cvt_pk_bf16_f32 v4, v4, v5
	ds_read2_b32 v[6:7], v40 offset0:66 offset1:99
	v_add3_u32 v13, v13, s5, v14
	s_waitcnt lgkmcnt(0)
	v_cvt_pk_bf16_f32 v5, v6, v7
	ds_read2_b32 v[6:7], v40 offset0:132 offset1:165
	v_lshl_add_u64 v[12:13], v[12:13], 1, v[10:11]
	s_waitcnt lgkmcnt(0)
	v_cvt_pk_bf16_f32 v6, v6, v7
	ds_read2_b32 v[8:9], v40 offset0:198 offset1:231
	s_waitcnt lgkmcnt(0)
	v_cvt_pk_bf16_f32 v7, v8, v9
	s_cmp_eq_u32 s100, 1
	s_cbranch_scc1 .Lwdn_0
	global_store_dwordx4 v[12:13], v[4:7], off
	s_branch .Lwdn_0x
.Lwdn_0:
	global_store_dwordx4 v[120:121], v[4:7], off
.Lwdn_0x:
	v_or_b32_e32 v12, s10, v41
	v_mul_lo_u32 v14, s9, v12
	v_mad_u64_u32 v[12:13], s[34:35], s8, v12, 0
	ds_read2_b32 v[8:9], v40 offset0:8 offset1:41
	s_waitcnt lgkmcnt(0)
	v_cvt_pk_bf16_f32 v4, v8, v9
	ds_read2_b32 v[6:7], v40 offset0:74 offset1:107
	v_add3_u32 v13, v13, s5, v14
	s_waitcnt lgkmcnt(0)
	v_cvt_pk_bf16_f32 v5, v6, v7
	ds_read2_b32 v[6:7], v40 offset0:140 offset1:173
	v_lshl_add_u64 v[12:13], v[12:13], 1, v[10:11]
	s_waitcnt lgkmcnt(0)
	v_cvt_pk_bf16_f32 v6, v6, v7
	ds_read2_b32 v[8:9], v40 offset0:206 offset1:239
	s_waitcnt lgkmcnt(0)
	v_cvt_pk_bf16_f32 v7, v8, v9
	s_cmp_eq_u32 s100, 1
	s_cbranch_scc1 .Lwdn_1
	global_store_dwordx4 v[12:13], v[4:7], off
	s_branch .Lwdn_1x
.Lwdn_1:
	global_store_dwordx4 v[120:121], v[4:7], off offset:64
.Lwdn_1x:
	v_or_b32_e32 v12, s10, v42
	ds_read2_b32 v[8:9], v40 offset0:16 offset1:49
	s_waitcnt lgkmcnt(0)
	v_cvt_pk_bf16_f32 v4, v8, v9
	ds_read2_b32 v[6:7], v40 offset0:82 offset1:115
	v_mul_lo_u32 v14, s9, v12
	v_mad_u64_u32 v[12:13], s[34:35], s8, v12, 0
	s_waitcnt lgkmcnt(0)
	v_cvt_pk_bf16_f32 v5, v6, v7
	ds_read2_b32 v[6:7], v40 offset0:148 offset1:181
	v_add3_u32 v13, v13, s5, v14
	s_waitcnt lgkmcnt(0)
	v_cvt_pk_bf16_f32 v6, v6, v7
	ds_read2_b32 v[8:9], v40 offset0:214 offset1:247
	s_waitcnt lgkmcnt(0)
	v_cvt_pk_bf16_f32 v7, v8, v9
	v_lshl_add_u64 v[12:13], v[12:13], 1, v[10:11]
	ds_read2_b32 v[8:9], v40 offset0:24 offset1:57
	s_cmp_eq_u32 s100, 1
	s_cbranch_scc1 .Lwdn_2
	global_store_dwordx4 v[12:13], v[4:7], off
	s_branch .Lwdn_2x
.Lwdn_2:
	global_store_dwordx4 v[120:121], v[4:7], off offset:128
.Lwdn_2x:
	v_or_b32_e32 v12, s10, v43
	v_mul_lo_u32 v13, s9, v12
	s_waitcnt lgkmcnt(0)
	v_cvt_pk_bf16_f32 v4, v8, v9
	ds_read2_b32 v[6:7], v40 offset0:90 offset1:123
	s_waitcnt lgkmcnt(0)
	v_cvt_pk_bf16_f32 v5, v6, v7
	ds_read2_b32 v[6:7], v40 offset0:156 offset1:189
	s_waitcnt lgkmcnt(0)
	v_cvt_pk_bf16_f32 v6, v6, v7
	ds_read2_b32 v[8:9], v40 offset0:222 offset1:255
	s_waitcnt lgkmcnt(0)
	v_cvt_pk_bf16_f32 v7, v8, v9
	v_mad_u64_u32 v[8:9], s[8:9], s8, v12, 0
	v_add3_u32 v9, v9, s5, v13
	v_lshl_add_u64 v[8:9], v[8:9], 1, v[10:11]
	s_cmp_eq_u32 s100, 1
	s_cbranch_scc1 .Lwdn_3
	global_store_dwordx4 v[8:9], v[4:7], off
	s_branch .Lwdn_3x
.Lwdn_3:
	global_store_dwordx4 v[120:121], v[4:7], off offset:192
.Lwdn_3x:
	s_waitcnt lgkmcnt(0)
	s_add_i32 s4, s4, 1
	s_cmp_lg_u32 s4, 16
	s_cbranch_scc0 .LBB0_241

;     __device__ bool next(int i, Unit& u) const { return at((long)i * G + c, u); }
;     __device__ bool next(int i, Unit& u) const { if (i > 0) return false; u.pm = pm; u.pn = pn; u.g = 0; u.nt = nt; u.k0 = 0; u.part = -1; return true; }
; #define PG8_STAGE(bufoff, gbase, voff) do { _Pragma("unroll") for (int _i = 0; _i < 2; ++_i) \
;         __builtin_amdgcn_global_load_lds((const unsigned*)((const char*)(gbase) + (voff)[_i]), (LAS unsigned*)(lds + (bufoff) + ldsw + _i * 8192), 16, 0, 0); } while (0)
; #define PG8_WAIT_V(n) asm volatile("s_waitcnt vmcnt(" #n ")" ::: "memory")
; #define PG8_BAR __builtin_amdgcn_s_barrier()
; template <class Epi, class Sched>
; __device__ __forceinline__ void gemm_phase(LAS unsigned char* lds, const Gemm g, const Sched& S, const Epi& E) {
;     ...
;     unsigned voffA[2], voffB[2];
; #pragma unroll
;     for (int i = 0; i < 2; ++i) { int R, C; stage_rc(tid * 16 + i * 8192, R, C); const int Rb = Epi::PERM ? ((R & ~31) + perm32(R & 31)) : R;
;         voffA[i] = (unsigned)(R * g.lda + C) * 2u; voffB[i] = (unsigned)(Rb * g.ldb + C) * 2u; }
;     const size_t kstep = (size_t)(BK * 2);
;     const size_t hstepA = (size_t)HALF * g.lda * 2, hstepB = (size_t)HALF * g.ldb * 2;
;     const unsigned ldsw = (unsigned)wid * 1024u;
;     const int aoff = lds_byte(wr * 64 + fr, fq * 8), boff = lds_byte(wc * 32 + fr, fq * 8);
;     ...
;     Unit cur, nxt; int ui = 0;
;     if (!S.next(0, cur)) return;
;     f32x4 acc[2][2][4][2];
; #pragma unroll
;     for (int a = 0; a < 2; ++a)
; #pragma unroll
;         for (int b = 0; b < 2; ++b)
; #pragma unroll
;             for (int m = 0; m < 4; ++m)
; #pragma unroll
;                 for (int n = 0; n < 2; ++n) acc[a][b][m][n] = (f32x4){0.f, 0.f, 0.f, 0.f};
;     bf16x8 At[4][2], B0[2][2], B1[2][2];
;     const char* cA = PG8_ABASE(cur); const char* cB = PG8_BBASE(cur);
;     PG8_STAGE(PG8_SB(0, 0), cB, voffB); PG8_STAGE(PG8_SB(0, 1), cB + hstepB, voffB); PG8_STAGE(PG8_SA(0, 0), cA, voffA); PG8_STAGE(PG8_SA(0, 1), cA + hstepA, voffA);
;     if (wr == 1) PG8_BAR;
;     PG8_WAIT_V(2); PG8_BAR;
;     PG8_STAGE(PG8_SB(1, 0), cB + kstep, voffB); PG8_STAGE(PG8_SA(1, 0), cA + kstep, voffA); PG8_STAGE(PG8_SB(1, 1), cB + hstepB + kstep, voffB);
;     PG8_WAIT_V(6); PG8_BAR;
.LBB0_905:
	s_andn2_b64 vcc, exec, s[6:7]
	s_cbranch_vccnz .LBB0_953
	v_lshrrev_b32_e32 v2, 1, v136
	v_lshrrev_b32_e32 v3, 5, v136
	v_and_b32_e32 v2, 24, v2
	v_and_b32_e32 v3, 4, v3
	v_bfe_u32 v4, v136, 2, 2
	v_lshlrev_b32_e32 v0, 4, v136
	s_waitcnt lgkmcnt(0)
	v_and_b32_e32 v1, 32, v136
	v_bfe_u32 v10, v136, 2, 4
	v_or3_b32 v2, v3, v4, v2
	v_lshrrev_b32_e32 v3, 3, v136
	s_movk_i32 s6, 0x70
	v_bitop3_b32 v8, v0, v1, 48 bitop3:0x6c
	v_and_b32_e32 v9, 64, v136
	v_and_or_b32 v4, v3, s6, v10
	s_movk_i32 s6, 0x60
	v_add_u32_e32 v11, 0x2000, v0
	v_or_b32_e32 v1, v8, v9
	v_and_or_b32 v3, v3, s6, v2
	v_lshrrev_b32_e32 v0, 7, v11
	s_movk_i32 s6, 0xf0
	v_lshl_or_b32 v156, v3, 14, v1
	v_and_b32_e32 v240, 64, v156
	v_lshlrev_b32_e32 v240, 4, v240
	v_lshrrev_b32_e32 v241, 7, v136
	v_lshl_or_b32 v240, v241, 18, v240
	v_and_b32_e32 v241, 63, v136
	v_lshl_or_b32 v156, v241, 4, v240
	v_and_or_b32 v3, v0, s6, v10
	s_movk_i32 s6, 0xe0
	v_and_or_b32 v0, v0, s6, v2
	s_lshr_b32 s6, s2, 6
	s_ashr_i32 s19, s18, 31
	s_lshr_b32 s5, s2, 8
	s_lshl_b32 s39, s6, 10
	s_lshl_b64 s[8:9], s[18:19], 22
	v_readlane_b32 s20, v242, 6
	v_readlane_b32 s21, v242, 7
	s_add_u32 s7, s20, s8
	s_addc_u32 s13, s21, s9
	s_ashr_i32 s17, s16, 31
	s_lshl_b64 s[8:9], s[16:17], 22
	s_add_u32 s8, s90, s8
	s_addc_u32 s9, s91, s9
	s_lshl_b64 s[100:101], s[0:1], 4
	s_add_u32 s66, s8, s100
	s_addc_u32 s67, s9, s101
	s_add_i32 s17, s39, 0
	s_add_i32 m0, s17, 0x10000
	v_lshl_or_b32 v160, v0, 14, v1
	v_and_b32_e32 v240, 64, v160
	v_lshlrev_b32_e32 v240, 4, v240
	v_lshrrev_b32_e32 v241, 7, v136
	v_lshl_or_b32 v240, v241, 18, v240
	v_and_b32_e32 v241, 63, v136
	v_lshl_or_b32 v160, v241, 4, v240
	v_add_u32_e32 v160, 0x100000, v160
	global_load_lds_dwordx4 v156, s[66:67]
	s_add_i32 m0, s17, 0x12000
	s_add_u32 s8, s66, 0x200000
	global_load_lds_dwordx4 v160, s[66:67]
	s_addc_u32 s9, s67, 0
	s_add_i32 m0, s17, 0x14000
	v_lshl_or_b32 v154, v4, 14, v1
	v_and_b32_e32 v240, 0x1c0000, v154
	v_and_b32_e32 v241, 64, v154
	v_lshl_or_b32 v240, v241, 4, v240
	v_and_b32_e32 v241, 63, v136
	v_lshl_or_b32 v154, v241, 4, v240
	global_load_lds_dwordx4 v156, s[8:9]
	s_add_i32 m0, s17, 0x16000
	v_lshl_or_b32 v158, v3, 14, v1
	v_and_b32_e32 v240, 0x1c0000, v158
	v_and_b32_e32 v241, 64, v158
	v_lshl_or_b32 v240, v241, 4, v240
	v_and_b32_e32 v241, 63, v136
	v_lshl_or_b32 v158, v241, 4, v240
	global_load_lds_dwordx4 v160, s[8:9]
	s_lshl_b64 s[100:101], s[0:1], 4
	s_add_u32 s8, s7, s100
	s_addc_u32 s9, s13, s101
	s_add_i32 s72, s17, 0x2000
	s_mov_b32 m0, s17
	s_add_u32 s0, s8, 0x200000
	global_load_lds_dwordx4 v154, s[8:9]
	s_mov_b32 m0, s72
	s_addc_u32 s1, s9, 0
	s_add_i32 s73, s17, 0x4000
	global_load_lds_dwordx4 v158, s[8:9]
	s_mov_b32 m0, s73
	s_add_i32 s76, s17, 0x6000
	global_load_lds_dwordx4 v154, s[0:1]
	s_mov_b32 m0, s76
	v_mov_b32_e32 v163, 0
	global_load_lds_dwordx4 v158, s[0:1]
	v_mov_b32_e32 v157, v163
	v_mov_b32_e32 v161, v163
	v_mov_b32_e32 v155, v163
	v_mov_b32_e32 v159, v163
	s_cmp_eq_u32 s5, 1
	s_mov_b32 s75, s87
	s_mov_b32 s13, 0
	v_lshl_add_u64 v[6:7], s[66:67], 0, v[156:157]
	v_lshl_add_u64 v[4:5], s[66:67], 0, v[160:161]
	v_lshl_add_u64 v[0:1], s[8:9], 0, v[154:155]
	s_cselect_b64 s[20:21], -1, 0
	s_cmp_lg_u32 s5, 1
	v_lshl_add_u64 v[2:3], s[8:9], 0, v[158:159]
	s_cbranch_scc1 .LBB0_908
.LBB0_908:
	s_lshl_b32 s0, s6, 5
	s_and_b32 s19, s0, 0x60
	s_lshl_b32 s7, s5, 13
	s_lshl_b32 s6, s19, 7
	s_add_u32 s22, s30, 0xc8000
	s_addc_u32 s23, s31, 0
	s_add_u32 s77, s30, 0xea000
	s_mov_b64 s[24:25], 0x800
	s_mov_b64 s[98:99], 0x800
	s_addc_u32 s78, s31, 0
	s_add_i32 m0, s17, 0x18000
	v_lshl_add_u64 v[6:7], v[6:7], 0, s[24:25]
	s_waitcnt vmcnt(2)
	s_barrier
	global_load_lds_dwordx4 v[6:7], off
	v_lshl_add_u64 v[4:5], v[4:5], 0, s[24:25]
	s_add_i32 m0, s17, 0x1a000
	s_add_i32 s79, s17, 0x8000
	s_add_i32 s80, s17, 0xa000
	global_load_lds_dwordx4 v[4:5], off
	v_lshl_add_u64 v[0:1], v[0:1], 0, s[98:99]
	s_mov_b32 m0, s79
	s_add_u32 s0, s66, 0x200800
	global_load_lds_dwordx4 v[0:1], off
	v_lshl_add_u64 v[0:1], v[2:3], 0, s[98:99]
	s_mov_b32 m0, s80
	s_addc_u32 s1, s67, 0
	global_load_lds_dwordx4 v[0:1], off
	s_add_i32 m0, s17, 0x1c000
	v_lshl_add_u64 v[0:1], s[0:1], 0, v[156:157]
	global_load_lds_dwordx4 v[0:1], off
	v_lshl_add_u64 v[0:1], s[0:1], 0, v[160:161]
	s_add_i32 m0, s17, 0x1e000
	v_bfe_u32 v2, v136, 4, 2
	global_load_lds_dwordx4 v[0:1], off
	v_and_b32_e32 v1, 15, v136
	v_lshlrev_b32_e32 v3, 4, v2
	v_lshlrev_b32_e32 v5, 2, v136
	v_lshlrev_b32_e32 v6, 6, v136
	s_movk_i32 s0, 0x3c0
	v_lshl_or_b32 v164, s5, 6, v1
	v_lshl_or_b32 v4, v1, 6, v3
	v_and_b32_e32 v5, 32, v5
	v_and_or_b32 v3, v6, s0, v3
	v_or_b32_e32 v1, v2, v1
	v_bitop3_b32 v4, v4, s7, v5 bitop3:0xde
	v_bitop3_b32 v153, s6, v3, v5 bitop3:0xf6
	v_and_b32_e32 v153, 0xfffff000, v153
	v_and_b32_e32 v240, 63, v136
	v_lshl_or_b32 v153, v240, 4, v153
	v_cmp_eq_u32_e64 s[6:7], 0, v1
	v_lshlrev_b32_e32 v1, 11, v136
	v_lshlrev_b32_e32 v0, 3, v2
	v_cmp_eq_u32_e64 s[0:1], 0, v2
	v_and_b32_e32 v1, 0x1c0000, v1
	v_lshlrev_b32_e32 v2, 14, v10
	v_or3_b32 v1, v8, v1, v2
	v_add_u32_e32 v168, v1, v9
	v_and_b32_e32 v240, 0x1c0000, v168
	v_and_b32_e32 v241, 64, v168
	v_lshl_or_b32 v240, v241, 4, v240
	v_and_b32_e32 v241, 63, v136
	v_lshl_or_b32 v168, v241, 4, v240
	v_lshlrev_b32_e32 v1, 7, v11
	s_waitcnt vmcnt(6)
	s_cmpk_lt_u32 s2, 0x100
	v_mov_b32_e32 v165, v163
	v_and_b32_e32 v1, 0x3c0000, v1
	s_cselect_b64 s[36:37], -1, 0
	v_lshlrev_b64 v[166:167], 13, v[164:165]
	v_or_b32_e32 v165, s19, v0
	v_or3_b32 v1, v8, v1, v2
	s_add_i32 s81, 0, 0x10000
	s_add_i32 s82, 0, 0x14000
	v_lshlrev_b32_e32 v162, 2, v0
	s_mov_b32 s42, 0xf0060000
	s_mov_b32 s44, 0xf0100000
	s_mov_b32 s48, 0xf0120000
	s_mov_b32 s50, 0xf0140000
	s_mov_b32 s52, 0xf0160000
	v_mbcnt_lo_u32_b32 v0, -1, 0
	v_mov_b32_e32 v169, v163
	v_add_u32_e32 v170, v1, v9
	v_and_b32_e32 v240, 0x1c0000, v170
	v_and_b32_e32 v241, 64, v170
	v_lshl_or_b32 v240, v241, 4, v240
	v_and_b32_e32 v241, 63, v136
	v_lshl_or_b32 v170, v241, 4, v240
	v_mov_b32_e32 v171, v163
	v_add_u32_e32 v208, s81, v153
	v_add_u32_e32 v209, s82, v153
	v_and_b32_e32 v210, 0xffffe000, v4
	v_and_b32_e32 v240, 63, v136
	v_lshl_or_b32 v210, v240, 4, v210
	s_mov_b32 s38, 0x3a000000
	s_mov_b32 s83, 0x800000
	s_lshl_b32 s40, s19, 2
	s_mov_b32 s84, 0xf0040000
	s_mov_b32 s43, -1
	s_mov_b32 s85, 0xf0060000
	s_mov_b32 s45, -1
	s_mov_b32 s86, 0xf0100000
	s_mov_b32 s49, -1
	s_mov_b32 s33, 0xf0120000
	s_mov_b32 s51, -1
	s_mov_b32 s53, -1
	v_mbcnt_hi_u32_b32 v211, -1, v0
	s_mov_b32 s87, s13
	s_barrier
	s_branch .LBB0_911

;     __device__ bool next(int i, Unit& u) const { return at((long)i * G + c, u); }
;     __device__ bool next(int i, Unit& u) const { if (i > 0) return false; u.pm = pm; u.pn = pn; u.g = 0; u.nt = nt; u.k0 = 0; u.part = -1; return true; }
; #define PG8_STAGE(bufoff, gbase, voff) do { _Pragma("unroll") for (int _i = 0; _i < 2; ++_i) \
;         __builtin_amdgcn_global_load_lds((const unsigned*)((const char*)(gbase) + (voff)[_i]), (LAS unsigned*)(lds + (bufoff) + ldsw + _i * 8192), 16, 0, 0); } while (0)
; #define PG8_LDA(dst, b, h) do { _Pragma("unroll") for (int m = 0; m < 4; ++m) _Pragma("unroll") for (int k = 0; k < 2; ++k) dst[m][k] = *(const LAS bf16x8*)(lds + PG8_SA(b, h) + aoff + m * 2048 + k * 1024); } while (0)
; #define PG8_LDB(dst, b, h) do { _Pragma("unroll") for (int n = 0; n < 2; ++n) _Pragma("unroll") for (int k = 0; k < 2; ++k) dst[n][k] = *(const LAS bf16x8*)(lds + PG8_SB(b, h) + boff + n * 2048 + k * 1024); } while (0)
; #define PG8_BAR __builtin_amdgcn_s_barrier()
; #define PG8_SCHED __builtin_amdgcn_sched_barrier(0)
; template <class Epi, class Sched>
; __device__ __forceinline__ void gemm_phase(LAS unsigned char* lds, const Gemm g, const Sched& S, const Epi& E) {
;     ...
;     for (;;) {
;         const bool has_next = S.next(ui + 1, nxt);
;         const char* nA = has_next ? PG8_ABASE(nxt) : cA; const char* nB = has_next ? PG8_BBASE(nxt) : cB;
;         const int nt = cur.nt;
;         for (int t = 0; t < nt; t += 2) {
;             const bool last = (t == nt - 2);
;             const char* a1 = cA + (size_t)(t + 1) * kstep;
;             const char* a2 = last ? nA : cA + (size_t)(t + 2) * kstep; const char* b2 = last ? nB : cB + (size_t)(t + 2) * kstep;
;             const char* a3 = a2 + kstep; const char* b3 = b2 + kstep;
;             PG8_LDB(B0, 0, 0); PG8_LDB(B1, 0, 1); PG8_SCHED; PG8_LDA(At, 0, 0); PG8_STAGE(PG8_SA(1, 1), a1 + hstepA, voffA);
;     ...
; #pragma unroll
;         for (int a = 0; a < 2; ++a)
; #pragma unroll
;             for (int b = 0; b < 2; ++b)
; #pragma unroll
;                 for (int m = 0; m < 4; ++m)
; #pragma unroll
;                     for (int n = 0; n < 2; ++n) acc[a][b][m][n] = (f32x4){0.f, 0.f, 0.f, 0.f};
;         cur = nxt; cA = nA; cB = nB; ++ui;
;         if (wr == 1) PG8_BAR;
.LBB0_916:
	s_ashr_i32 s55, s54, 31
	s_ashr_i32 s57, s56, 31
	s_lshl_b64 s[34:35], s[56:57], 7
	s_lshl_b64 s[46:47], s[54:55], 22
	v_readlane_b32 s62, v242, 6
	v_readlane_b32 s63, v242, 7
	s_add_u32 s2, s62, s46
	s_addc_u32 s5, s63, s47
	s_lshl_b64 s[100:101], s[56:57], 11
	s_add_u32 s62, s2, s100
	s_addc_u32 s63, s5, s101
	s_and_b64 s[46:47], s[60:61], exec
	s_cselect_b32 s2, s63, s9
	s_cselect_b32 s5, s62, s8
	s_ashr_i32 s59, s58, 31
	s_lshl_b64 s[46:47], s[58:59], 22
	s_add_u32 s19, s90, s46
	s_addc_u32 s41, s91, s47
	s_add_u32 s64, s19, s100
	s_addc_u32 s65, s41, s101
	s_and_b64 s[34:35], s[60:61], exec
	s_cselect_b32 s19, s65, s67
	s_cselect_b32 s34, s64, s66
	s_add_i32 s35, s4, -2
	s_add_u32 s8, s8, 0x200800
	s_addc_u32 s9, s9, 0
	s_add_u32 s41, s66, 0x1000
	v_mov_b32_e32 v0, 0
	s_mov_b64 s[92:93], s[90:91]
	s_addc_u32 s46, s67, 0
	s_mov_b32 s47, 0
	v_mov_b32_e32 v1, v0
	v_mov_b32_e32 v2, v0
	v_mov_b32_e32 v3, v0
	v_mov_b32_e32 v4, v0
	v_mov_b32_e32 v5, v0
	v_mov_b32_e32 v6, v0
	v_mov_b32_e32 v7, v0
	v_mov_b32_e32 v8, v0
	v_mov_b32_e32 v9, v0
	v_mov_b32_e32 v10, v0
	v_mov_b32_e32 v11, v0
	v_mov_b32_e32 v12, v0
	v_mov_b32_e32 v13, v0
	v_mov_b32_e32 v14, v0
	v_mov_b32_e32 v15, v0
	v_mov_b32_e32 v20, v0
	v_mov_b32_e32 v21, v0
	v_mov_b32_e32 v22, v0
	v_mov_b32_e32 v23, v0
	v_mov_b32_e32 v28, v0
	v_mov_b32_e32 v29, v0
	v_mov_b32_e32 v30, v0
	v_mov_b32_e32 v31, v0
	v_mov_b32_e32 v36, v0
	v_mov_b32_e32 v37, v0
	v_mov_b32_e32 v38, v0
	v_mov_b32_e32 v39, v0
	v_mov_b32_e32 v44, v0
	v_mov_b32_e32 v45, v0
	v_mov_b32_e32 v46, v0
	v_mov_b32_e32 v47, v0
	v_mov_b32_e32 v16, v0
	v_mov_b32_e32 v17, v0
	v_mov_b32_e32 v18, v0
	v_mov_b32_e32 v19, v0
	s_waitcnt vmcnt(0)
	v_mov_b32_e32 v24, v0
	v_mov_b32_e32 v25, v0
	v_mov_b32_e32 v26, v0
	v_mov_b32_e32 v27, v0
	v_mov_b32_e32 v32, v0
	v_mov_b32_e32 v33, v0
	v_mov_b32_e32 v34, v0
	v_mov_b32_e32 v35, v0
	v_mov_b32_e32 v40, v0
	v_mov_b32_e32 v41, v0
	v_mov_b32_e32 v42, v0
	v_mov_b32_e32 v43, v0
	v_mov_b32_e32 v48, v0
	v_mov_b32_e32 v49, v0
	v_mov_b32_e32 v50, v0
	v_mov_b32_e32 v51, v0
	v_mov_b32_e32 v52, v0
	v_mov_b32_e32 v53, v0
	v_mov_b32_e32 v54, v0
	v_mov_b32_e32 v55, v0
	v_mov_b32_e32 v56, v0
	v_mov_b32_e32 v57, v0
	v_mov_b32_e32 v58, v0
	v_mov_b32_e32 v59, v0
	v_mov_b32_e32 v60, v0
	v_mov_b32_e32 v61, v0
	v_mov_b32_e32 v62, v0
	v_mov_b32_e32 v63, v0
	v_mov_b32_e32 v64, v0
	v_mov_b32_e32 v65, v0
	v_mov_b32_e32 v66, v0
	v_mov_b32_e32 v67, v0
	v_mov_b32_e32 v68, v0
	v_mov_b32_e32 v69, v0
	v_mov_b32_e32 v70, v0
	v_mov_b32_e32 v71, v0
	v_mov_b32_e32 v72, v0
	v_mov_b32_e32 v73, v0
	v_mov_b32_e32 v74, v0
	v_mov_b32_e32 v75, v0
	v_mov_b32_e32 v76, v0
	v_mov_b32_e32 v77, v0
	v_mov_b32_e32 v78, v0
	v_mov_b32_e32 v79, v0
	v_mov_b32_e32 v84, v0
	v_mov_b32_e32 v85, v0
	v_mov_b32_e32 v86, v0
	v_mov_b32_e32 v87, v0
	v_mov_b32_e32 v92, v0
	v_mov_b32_e32 v93, v0
	v_mov_b32_e32 v94, v0
	v_mov_b32_e32 v95, v0
	v_mov_b32_e32 v100, v0
	v_mov_b32_e32 v101, v0
	v_mov_b32_e32 v102, v0
	v_mov_b32_e32 v103, v0
	v_mov_b32_e32 v108, v0
	v_mov_b32_e32 v109, v0
	v_mov_b32_e32 v110, v0
	v_mov_b32_e32 v111, v0
	v_mov_b32_e32 v80, v0
	v_mov_b32_e32 v81, v0
	v_mov_b32_e32 v82, v0
	v_mov_b32_e32 v83, v0
	v_mov_b32_e32 v88, v0
	v_mov_b32_e32 v89, v0
	v_mov_b32_e32 v90, v0
	v_mov_b32_e32 v91, v0
	v_mov_b32_e32 v96, v0
	v_mov_b32_e32 v97, v0
	v_mov_b32_e32 v98, v0
	v_mov_b32_e32 v99, v0
	v_mov_b32_e32 v104, v0
	v_mov_b32_e32 v105, v0
	v_mov_b32_e32 v106, v0
	v_mov_b32_e32 v107, v0
	v_mov_b32_e32 v112, v0
	v_mov_b32_e32 v113, v0
	v_mov_b32_e32 v114, v0
	v_mov_b32_e32 v115, v0
	v_mov_b32_e32 v116, v0
	v_mov_b32_e32 v117, v0
	v_mov_b32_e32 v118, v0
	v_mov_b32_e32 v119, v0
	v_mov_b32_e32 v120, v0
	v_mov_b32_e32 v121, v0
	v_mov_b32_e32 v122, v0
	v_mov_b32_e32 v123, v0
	v_mov_b32_e32 v124, v0
	v_mov_b32_e32 v125, v0
	v_mov_b32_e32 v126, v0
	v_mov_b32_e32 v127, v0
	s_cmp_lg_u64 s[20:21], 0
	s_cbranch_scc0 .Ledge_p8
	s_barrier
.Ledge_p8:
.LBB0_917:
	ds_read_b128 v[128:131], v208
	ds_read_b128 v[132:135], v208 offset:1024
	ds_read_b128 v[136:139], v208 offset:2048
	ds_read_b128 v[140:143], v208 offset:3072
	ds_read_b128 v[144:147], v209
	ds_read_b128 v[148:151], v209 offset:1024
	ds_read_b128 v[172:175], v209 offset:2048
	ds_read_b128 v[176:179], v209 offset:3072
	s_add_i32 s55, s47, 2
	s_add_u32 s57, s8, 0xffe00800
	s_addc_u32 s59, s9, -1
	s_cmp_eq_u32 s35, s47
	s_cselect_b32 s71, s2, s59
	s_cselect_b32 s70, s5, s57
	s_cselect_b32 s67, s19, s46
	s_cselect_b32 s66, s34, s41
	v_lshl_add_u64 v[216:217], s[8:9], 0, v[168:169]
	s_add_i32 m0, s17, 0xc000
	ds_read_b128 v[180:183], v210
	ds_read_b128 v[184:187], v210 offset:1024
	ds_read_b128 v[188:191], v210 offset:2048
	ds_read_b128 v[192:195], v210 offset:3072
	ds_read_b128 v[196:199], v210 offset:4096
	ds_read_b128 v[200:203], v210 offset:5120
	ds_read_b128 v[204:207], v210 offset:6144
	ds_read_b128 v[212:215], v210 offset:7168
	global_load_lds_dwordx4 v[216:217], off
	v_lshl_add_u64 v[216:217], s[8:9], 0, v[170:171]
	s_add_i32 m0, s17, 0xe000
	s_nop 0
	global_load_lds_dwordx4 v[216:217], off
	s_waitcnt vmcnt(8)
	s_waitcnt lgkmcnt(0)
	s_barrier
; #define PG8_STAGE(bufoff, gbase, voff) do { _Pragma("unroll") for (int _i = 0; _i < 2; ++_i) \
;         __builtin_amdgcn_global_load_lds((const unsigned*)((const char*)(gbase) + (voff)[_i]), (LAS unsigned*)(lds + (bufoff) + ldsw + _i * 8192), 16, 0, 0); } while (0)
; #define PG8_LDA(dst, b, h) do { _Pragma("unroll") for (int m = 0; m < 4; ++m) _Pragma("unroll") for (int k = 0; k < 2; ++k) dst[m][k] = *(const LAS bf16x8*)(lds + PG8_SA(b, h) + aoff + m * 2048 + k * 1024); } while (0)
; #define PG8_LDB(dst, b, h) do { _Pragma("unroll") for (int n = 0; n < 2; ++n) _Pragma("unroll") for (int k = 0; k < 2; ++k) dst[n][k] = *(const LAS bf16x8*)(lds + PG8_SB(b, h) + boff + n * 2048 + k * 1024); } while (0)
; #define PG8_MMA(ai, bj, At, Bt) do { __builtin_amdgcn_s_setprio(1); _Pragma("unroll") for (int m = 0; m < 4; ++m) _Pragma("unroll") for (int n = 0; n < 2; ++n) _Pragma("unroll") for (int k = 0; k < 2; ++k) \
;         acc[ai][bj][m][n] = __builtin_amdgcn_mfma_f32_16x16x32_bf16(Bt[n][k], At[m][k], acc[ai][bj][m][n], 0, 0, 0); __builtin_amdgcn_s_setprio(0); } while (0)
; #define PG8_WAIT_V(n) asm volatile("s_waitcnt vmcnt(" #n ")" ::: "memory")
; #define PG8_WAIT_L(n) asm volatile("s_waitcnt lgkmcnt(" #n ")" ::: "memory")
; #define PG8_BAR __builtin_amdgcn_s_barrier()
; #define PG8_SCHED __builtin_amdgcn_sched_barrier(0)
; template <class Epi, class Sched>
; __device__ __forceinline__ void gemm_phase(LAS unsigned char* lds, const Gemm g, const Sched& S, const Epi& E) {
;     ...
;             PG8_LDB(B0, 0, 0); PG8_LDB(B1, 0, 1); PG8_SCHED; PG8_LDA(At, 0, 0); PG8_STAGE(PG8_SA(1, 1), a1 + hstepA, voffA);
;             PG8_WAIT_V(8); PG8_WAIT_L(0); PG8_BAR; PG8_MMA(0, 0, At, B0); PG8_MMA(0, 1, At, B1); PG8_BAR; PG8_SCHED;
;             PG8_LDA(At, 0, 1); PG8_STAGE(PG8_SB(0, 0), b2, voffB); PG8_STAGE(PG8_SB(0, 1), b2 + hstepB, voffB); PG8_STAGE(PG8_SA(0, 0), a2, voffA);
;             PG8_WAIT_V(8); PG8_WAIT_L(0); PG8_BAR; PG8_MMA(1, 0, At, B0); PG8_MMA(1, 1, At, B1); PG8_BAR; PG8_SCHED;
	s_setprio 1
	s_waitcnt lgkmcnt(0)
	v_mfma_f32_16x16x32_bf16 v[124:127], v[128:131], v[180:183], v[124:127]
	v_mfma_f32_16x16x32_bf16 v[120:123], v[136:139], v[180:183], v[120:123]
	v_mfma_f32_16x16x32_bf16 v[116:119], v[128:131], v[188:191], v[116:119]
	v_mfma_f32_16x16x32_bf16 v[112:115], v[136:139], v[188:191], v[112:115]
	v_mfma_f32_16x16x32_bf16 v[104:107], v[128:131], v[196:199], v[104:107]
	v_mfma_f32_16x16x32_bf16 v[96:99], v[136:139], v[196:199], v[96:99]
	v_mfma_f32_16x16x32_bf16 v[88:91], v[128:131], v[204:207], v[88:91]
	v_mfma_f32_16x16x32_bf16 v[80:83], v[136:139], v[204:207], v[80:83]
	v_mfma_f32_16x16x32_bf16 v[124:127], v[132:135], v[184:187], v[124:127]
	v_mfma_f32_16x16x32_bf16 v[120:123], v[140:143], v[184:187], v[120:123]
	v_mfma_f32_16x16x32_bf16 v[116:119], v[132:135], v[192:195], v[116:119]
	v_mfma_f32_16x16x32_bf16 v[112:115], v[140:143], v[192:195], v[112:115]
	v_mfma_f32_16x16x32_bf16 v[104:107], v[132:135], v[200:203], v[104:107]
	v_mfma_f32_16x16x32_bf16 v[96:99], v[140:143], v[200:203], v[96:99]
	v_mfma_f32_16x16x32_bf16 v[88:91], v[132:135], v[212:215], v[88:91]
	v_mfma_f32_16x16x32_bf16 v[80:83], v[140:143], v[212:215], v[80:83]
	s_setprio 0
	s_setprio 1
	v_mfma_f32_16x16x32_bf16 v[108:111], v[144:147], v[180:183], v[108:111]
	v_mfma_f32_16x16x32_bf16 v[100:103], v[172:175], v[180:183], v[100:103]
	v_mfma_f32_16x16x32_bf16 v[92:95], v[144:147], v[188:191], v[92:95]
	v_mfma_f32_16x16x32_bf16 v[84:87], v[172:175], v[188:191], v[84:87]
	v_mfma_f32_16x16x32_bf16 v[76:79], v[144:147], v[196:199], v[76:79]
	v_mfma_f32_16x16x32_bf16 v[72:75], v[172:175], v[196:199], v[72:75]
	v_mfma_f32_16x16x32_bf16 v[68:71], v[144:147], v[204:207], v[68:71]
	v_mfma_f32_16x16x32_bf16 v[64:67], v[172:175], v[204:207], v[64:67]
	v_mfma_f32_16x16x32_bf16 v[108:111], v[148:151], v[184:187], v[108:111]
	v_mfma_f32_16x16x32_bf16 v[100:103], v[176:179], v[184:187], v[100:103]
	v_mfma_f32_16x16x32_bf16 v[92:95], v[148:151], v[192:195], v[92:95]
	v_mfma_f32_16x16x32_bf16 v[84:87], v[176:179], v[192:195], v[84:87]
	v_mfma_f32_16x16x32_bf16 v[76:79], v[148:151], v[200:203], v[76:79]
	v_mfma_f32_16x16x32_bf16 v[72:75], v[176:179], v[200:203], v[72:75]
	v_mfma_f32_16x16x32_bf16 v[68:71], v[148:151], v[212:215], v[68:71]
	v_mfma_f32_16x16x32_bf16 v[64:67], v[176:179], v[212:215], v[64:67]
	s_setprio 0
	s_barrier
	s_add_i32 s47, s81, s39
	v_lshl_add_u64 v[216:217], s[66:67], 0, v[156:157]
	s_mov_b32 m0, s47
	ds_read_b128 v[180:183], v210 offset:16384
	ds_read_b128 v[184:187], v210 offset:17408
	ds_read_b128 v[188:191], v210 offset:18432
	ds_read_b128 v[192:195], v210 offset:19456
	ds_read_b128 v[196:199], v210 offset:20480
	ds_read_b128 v[200:203], v210 offset:21504
	ds_read_b128 v[204:207], v210 offset:22528
	ds_read_b128 v[212:215], v210 offset:23552
	global_load_lds_dwordx4 v[216:217], off
	s_add_i32 m0, s47, 0x2000
	s_add_u32 s90, s66, 0x200000
	v_lshl_add_u64 v[218:219], s[66:67], 0, v[160:161]
	s_addc_u32 s91, s67, 0
	s_add_i32 s47, s82, s39
	global_load_lds_dwordx4 v[218:219], off
	v_lshl_add_u64 v[220:221], s[90:91], 0, v[156:157]
	s_mov_b32 m0, s47
	v_lshl_add_u64 v[222:223], s[70:71], 0, v[158:159]
	global_load_lds_dwordx4 v[220:221], off
	v_lshl_add_u64 v[220:221], s[90:91], 0, v[160:161]
	s_add_i32 m0, s47, 0x2000
	s_nop 0
	global_load_lds_dwordx4 v[220:221], off
	v_lshl_add_u64 v[220:221], s[70:71], 0, v[154:155]
	s_mov_b32 m0, s17
	s_nop 0
	global_load_lds_dwordx4 v[220:221], off
	s_mov_b32 m0, s72
	s_nop 0
	global_load_lds_dwordx4 v[222:223], off
	s_waitcnt vmcnt(8)
	s_waitcnt lgkmcnt(0)
	s_barrier
	s_setprio 1
	s_waitcnt lgkmcnt(0)
	v_mfma_f32_16x16x32_bf16 v[60:63], v[128:131], v[180:183], v[60:63]
	v_mfma_f32_16x16x32_bf16 v[56:59], v[136:139], v[180:183], v[56:59]
	v_mfma_f32_16x16x32_bf16 v[52:55], v[128:131], v[188:191], v[52:55]
	v_mfma_f32_16x16x32_bf16 v[48:51], v[136:139], v[188:191], v[48:51]
	v_mfma_f32_16x16x32_bf16 v[40:43], v[128:131], v[196:199], v[40:43]
	v_mfma_f32_16x16x32_bf16 v[32:35], v[136:139], v[196:199], v[32:35]
	v_mfma_f32_16x16x32_bf16 v[24:27], v[128:131], v[204:207], v[24:27]
	v_mfma_f32_16x16x32_bf16 v[16:19], v[136:139], v[204:207], v[16:19]
	v_mfma_f32_16x16x32_bf16 v[60:63], v[132:135], v[184:187], v[60:63]
	v_mfma_f32_16x16x32_bf16 v[56:59], v[140:143], v[184:187], v[56:59]
	v_mfma_f32_16x16x32_bf16 v[52:55], v[132:135], v[192:195], v[52:55]
	v_mfma_f32_16x16x32_bf16 v[48:51], v[140:143], v[192:195], v[48:51]
	v_mfma_f32_16x16x32_bf16 v[40:43], v[132:135], v[200:203], v[40:43]
	v_mfma_f32_16x16x32_bf16 v[32:35], v[140:143], v[200:203], v[32:35]
	v_mfma_f32_16x16x32_bf16 v[24:27], v[132:135], v[212:215], v[24:27]
	v_mfma_f32_16x16x32_bf16 v[16:19], v[140:143], v[212:215], v[16:19]
	s_setprio 0
	s_setprio 1
	v_mfma_f32_16x16x32_bf16 v[44:47], v[144:147], v[180:183], v[44:47]
	v_mfma_f32_16x16x32_bf16 v[36:39], v[172:175], v[180:183], v[36:39]
	v_mfma_f32_16x16x32_bf16 v[28:31], v[144:147], v[188:191], v[28:31]
	v_mfma_f32_16x16x32_bf16 v[20:23], v[172:175], v[188:191], v[20:23]
	v_mfma_f32_16x16x32_bf16 v[12:15], v[144:147], v[196:199], v[12:15]
	v_mfma_f32_16x16x32_bf16 v[8:11], v[172:175], v[196:199], v[8:11]
	v_mfma_f32_16x16x32_bf16 v[4:7], v[144:147], v[204:207], v[4:7]
	v_mfma_f32_16x16x32_bf16 v[0:3], v[172:175], v[204:207], v[0:3]
	v_mfma_f32_16x16x32_bf16 v[44:47], v[148:151], v[184:187], v[44:47]
	v_mfma_f32_16x16x32_bf16 v[36:39], v[176:179], v[184:187], v[36:39]
	v_mfma_f32_16x16x32_bf16 v[28:31], v[148:151], v[192:195], v[28:31]
	v_mfma_f32_16x16x32_bf16 v[20:23], v[176:179], v[192:195], v[20:23]
	v_mfma_f32_16x16x32_bf16 v[12:15], v[148:151], v[200:203], v[12:15]
	v_mfma_f32_16x16x32_bf16 v[8:11], v[176:179], v[200:203], v[8:11]
	v_mfma_f32_16x16x32_bf16 v[4:7], v[148:151], v[212:215], v[4:7]
	v_mfma_f32_16x16x32_bf16 v[0:3], v[176:179], v[212:215], v[0:3]
	s_setprio 0
	s_barrier
; #define PG8_STAGE(bufoff, gbase, voff) do { _Pragma("unroll") for (int _i = 0; _i < 2; ++_i) \
;         __builtin_amdgcn_global_load_lds((const unsigned*)((const char*)(gbase) + (voff)[_i]), (LAS unsigned*)(lds + (bufoff) + ldsw + _i * 8192), 16, 0, 0); } while (0)
; #define PG8_LDA(dst, b, h) do { _Pragma("unroll") for (int m = 0; m < 4; ++m) _Pragma("unroll") for (int k = 0; k < 2; ++k) dst[m][k] = *(const LAS bf16x8*)(lds + PG8_SA(b, h) + aoff + m * 2048 + k * 1024); } while (0)
; #define PG8_LDB(dst, b, h) do { _Pragma("unroll") for (int n = 0; n < 2; ++n) _Pragma("unroll") for (int k = 0; k < 2; ++k) dst[n][k] = *(const LAS bf16x8*)(lds + PG8_SB(b, h) + boff + n * 2048 + k * 1024); } while (0)
; #define PG8_MMA(ai, bj, At, Bt) do { __builtin_amdgcn_s_setprio(1); _Pragma("unroll") for (int m = 0; m < 4; ++m) _Pragma("unroll") for (int n = 0; n < 2; ++n) _Pragma("unroll") for (int k = 0; k < 2; ++k) \
;         acc[ai][bj][m][n] = __builtin_amdgcn_mfma_f32_16x16x32_bf16(Bt[n][k], At[m][k], acc[ai][bj][m][n], 0, 0, 0); __builtin_amdgcn_s_setprio(0); } while (0)
; #define PG8_WAIT_V(n) asm volatile("s_waitcnt vmcnt(" #n ")" ::: "memory")
; #define PG8_WAIT_L(n) asm volatile("s_waitcnt lgkmcnt(" #n ")" ::: "memory")
; #define PG8_BAR __builtin_amdgcn_s_barrier()
; #define PG8_SCHED __builtin_amdgcn_sched_barrier(0)
; template <class Epi, class Sched>
; __device__ __forceinline__ void gemm_phase(LAS unsigned char* lds, const Gemm g, const Sched& S, const Epi& E) {
;     ...
;             PG8_LDB(B0, 1, 0); PG8_LDB(B1, 1, 1); PG8_SCHED; PG8_LDA(At, 1, 0); PG8_STAGE(PG8_SA(0, 1), a2 + hstepA, voffA);
;             PG8_WAIT_V(8); PG8_WAIT_L(0); PG8_BAR; PG8_MMA(0, 0, At, B0); PG8_MMA(0, 1, At, B1); PG8_BAR; PG8_SCHED;
	s_add_i32 s47, 0, 0x18000
	s_add_i32 s57, 0, 0x1c000
	v_add_u32_e32 v140, s47, v153
	v_add_u32_e32 v176, s57, v153
	ds_read_b128 v[128:131], v140
	ds_read_b128 v[132:135], v140 offset:1024
	ds_read_b128 v[136:139], v140 offset:2048
	ds_read_b128 v[140:143], v140 offset:3072
	ds_read_b128 v[144:147], v176
	ds_read_b128 v[148:151], v176 offset:1024
	ds_read_b128 v[172:175], v176 offset:2048
	ds_read_b128 v[176:179], v176 offset:3072
	s_add_u32 s70, s70, 0x200000
	s_addc_u32 s71, s71, 0
	s_mov_b32 m0, s73
	v_lshl_add_u64 v[224:225], s[70:71], 0, v[154:155]
	ds_read_b128 v[180:183], v210 offset:32768
	ds_read_b128 v[184:187], v210 offset:33792
	ds_read_b128 v[188:191], v210 offset:34816
	ds_read_b128 v[192:195], v210 offset:35840
	ds_read_b128 v[196:199], v210 offset:36864
	ds_read_b128 v[200:203], v210 offset:37888
	ds_read_b128 v[204:207], v210 offset:38912
	ds_read_b128 v[212:215], v210 offset:39936
	global_load_lds_dwordx4 v[224:225], off
	v_lshl_add_u64 v[224:225], s[70:71], 0, v[158:159]
	s_mov_b32 m0, s76
	s_nop 0
	global_load_lds_dwordx4 v[224:225], off
	s_waitcnt vmcnt(8)
	s_waitcnt lgkmcnt(0)
	s_barrier
	s_setprio 1
	s_waitcnt lgkmcnt(0)
	v_mfma_f32_16x16x32_bf16 v[124:127], v[128:131], v[180:183], v[124:127]
	v_mfma_f32_16x16x32_bf16 v[120:123], v[136:139], v[180:183], v[120:123]
	v_mfma_f32_16x16x32_bf16 v[116:119], v[128:131], v[188:191], v[116:119]
	v_mfma_f32_16x16x32_bf16 v[112:115], v[136:139], v[188:191], v[112:115]
	v_mfma_f32_16x16x32_bf16 v[104:107], v[128:131], v[196:199], v[104:107]
	v_mfma_f32_16x16x32_bf16 v[96:99], v[136:139], v[196:199], v[96:99]
	v_mfma_f32_16x16x32_bf16 v[88:91], v[128:131], v[204:207], v[88:91]
	v_mfma_f32_16x16x32_bf16 v[80:83], v[136:139], v[204:207], v[80:83]
	v_mfma_f32_16x16x32_bf16 v[124:127], v[132:135], v[184:187], v[124:127]
	v_mfma_f32_16x16x32_bf16 v[120:123], v[140:143], v[184:187], v[120:123]
	v_mfma_f32_16x16x32_bf16 v[116:119], v[132:135], v[192:195], v[116:119]
	v_mfma_f32_16x16x32_bf16 v[112:115], v[140:143], v[192:195], v[112:115]
	v_mfma_f32_16x16x32_bf16 v[104:107], v[132:135], v[200:203], v[104:107]
	v_mfma_f32_16x16x32_bf16 v[96:99], v[140:143], v[200:203], v[96:99]
	v_mfma_f32_16x16x32_bf16 v[88:91], v[132:135], v[212:215], v[88:91]
	v_mfma_f32_16x16x32_bf16 v[80:83], v[140:143], v[212:215], v[80:83]
	s_setprio 0
	s_setprio 1
	v_mfma_f32_16x16x32_bf16 v[108:111], v[144:147], v[180:183], v[108:111]
	v_mfma_f32_16x16x32_bf16 v[100:103], v[172:175], v[180:183], v[100:103]
	v_mfma_f32_16x16x32_bf16 v[92:95], v[144:147], v[188:191], v[92:95]
	v_mfma_f32_16x16x32_bf16 v[84:87], v[172:175], v[188:191], v[84:87]
	v_mfma_f32_16x16x32_bf16 v[76:79], v[144:147], v[196:199], v[76:79]
	v_mfma_f32_16x16x32_bf16 v[72:75], v[172:175], v[196:199], v[72:75]
	v_mfma_f32_16x16x32_bf16 v[68:71], v[144:147], v[204:207], v[68:71]
	v_mfma_f32_16x16x32_bf16 v[64:67], v[172:175], v[204:207], v[64:67]
	v_mfma_f32_16x16x32_bf16 v[108:111], v[148:151], v[184:187], v[108:111]
	v_mfma_f32_16x16x32_bf16 v[100:103], v[176:179], v[184:187], v[100:103]
	v_mfma_f32_16x16x32_bf16 v[92:95], v[148:151], v[192:195], v[92:95]
	v_mfma_f32_16x16x32_bf16 v[84:87], v[176:179], v[192:195], v[84:87]
	v_mfma_f32_16x16x32_bf16 v[76:79], v[148:151], v[200:203], v[76:79]
	v_mfma_f32_16x16x32_bf16 v[72:75], v[176:179], v[200:203], v[72:75]
	v_mfma_f32_16x16x32_bf16 v[68:71], v[148:151], v[212:215], v[68:71]
	v_mfma_f32_16x16x32_bf16 v[64:67], v[176:179], v[212:215], v[64:67]
	s_setprio 0
	s_barrier
; #define PG8_STAGE(bufoff, gbase, voff) do { _Pragma("unroll") for (int _i = 0; _i < 2; ++_i) \
;         __builtin_amdgcn_global_load_lds((const unsigned*)((const char*)(gbase) + (voff)[_i]), (LAS unsigned*)(lds + (bufoff) + ldsw + _i * 8192), 16, 0, 0); } while (0)
; #define PG8_LDA(dst, b, h) do { _Pragma("unroll") for (int m = 0; m < 4; ++m) _Pragma("unroll") for (int k = 0; k < 2; ++k) dst[m][k] = *(const LAS bf16x8*)(lds + PG8_SA(b, h) + aoff + m * 2048 + k * 1024); } while (0)
; #define PG8_MMA(ai, bj, At, Bt) do { __builtin_amdgcn_s_setprio(1); _Pragma("unroll") for (int m = 0; m < 4; ++m) _Pragma("unroll") for (int n = 0; n < 2; ++n) _Pragma("unroll") for (int k = 0; k < 2; ++k) \
;         acc[ai][bj][m][n] = __builtin_amdgcn_mfma_f32_16x16x32_bf16(Bt[n][k], At[m][k], acc[ai][bj][m][n], 0, 0, 0); __builtin_amdgcn_s_setprio(0); } while (0)
; #define PG8_WAIT_V(n) asm volatile("s_waitcnt vmcnt(" #n ")" ::: "memory")
; #define PG8_WAIT_L(n) asm volatile("s_waitcnt lgkmcnt(" #n ")" ::: "memory")
; #define PG8_BAR __builtin_amdgcn_s_barrier()
; #define PG8_SCHED __builtin_amdgcn_sched_barrier(0)
; template <class Epi, class Sched>
; __device__ __forceinline__ void gemm_phase(LAS unsigned char* lds, const Gemm g, const Sched& S, const Epi& E) {
;     ...
;             PG8_LDA(At, 1, 1); PG8_STAGE(PG8_SB(1, 0), b3, voffB); PG8_STAGE(PG8_SB(1, 1), b3 + hstepB, voffB); PG8_STAGE(PG8_SA(1, 0), a3, voffA);
;             PG8_WAIT_V(8); PG8_WAIT_L(0); PG8_BAR; PG8_MMA(1, 0, At, B0); PG8_MMA(1, 1, At, B1); PG8_BAR; PG8_SCHED;
;         }
	s_add_i32 s47, s47, s39
	v_lshl_add_u64 v[216:217], v[216:217], 0, s[24:25]
	s_mov_b32 m0, s47
	ds_read_b128 v[180:183], v210 offset:49152
	ds_read_b128 v[184:187], v210 offset:50176
	ds_read_b128 v[188:191], v210 offset:51200
	ds_read_b128 v[192:195], v210 offset:52224
	ds_read_b128 v[196:199], v210 offset:53248
	ds_read_b128 v[200:203], v210 offset:54272
	ds_read_b128 v[204:207], v210 offset:55296
	ds_read_b128 v[212:215], v210 offset:56320
	global_load_lds_dwordx4 v[216:217], off
	s_add_i32 m0, s47, 0x2000
	s_add_u32 s66, s66, 0x200800
	v_lshl_add_u64 v[216:217], v[218:219], 0, s[24:25]
	s_addc_u32 s67, s67, 0
	s_add_i32 s47, s57, s39
	global_load_lds_dwordx4 v[216:217], off
	v_lshl_add_u64 v[216:217], s[66:67], 0, v[156:157]
	s_mov_b32 m0, s47
	s_nop 0
	global_load_lds_dwordx4 v[216:217], off
	v_lshl_add_u64 v[216:217], s[66:67], 0, v[160:161]
	s_add_i32 m0, s47, 0x2000
	s_nop 0
	global_load_lds_dwordx4 v[216:217], off
	v_lshl_add_u64 v[216:217], v[220:221], 0, s[98:99]
	s_mov_b32 m0, s79
	s_nop 0
	global_load_lds_dwordx4 v[216:217], off
	v_lshl_add_u64 v[216:217], v[222:223], 0, s[98:99]
	s_mov_b32 m0, s80
	s_nop 0
	global_load_lds_dwordx4 v[216:217], off
	s_waitcnt vmcnt(8)
	s_waitcnt lgkmcnt(0)
	s_barrier
	s_setprio 1
	s_waitcnt lgkmcnt(0)
	v_mfma_f32_16x16x32_bf16 v[60:63], v[128:131], v[180:183], v[60:63]
	v_mfma_f32_16x16x32_bf16 v[56:59], v[136:139], v[180:183], v[56:59]
	v_mfma_f32_16x16x32_bf16 v[52:55], v[128:131], v[188:191], v[52:55]
	v_mfma_f32_16x16x32_bf16 v[48:51], v[136:139], v[188:191], v[48:51]
	v_mfma_f32_16x16x32_bf16 v[40:43], v[128:131], v[196:199], v[40:43]
	v_mfma_f32_16x16x32_bf16 v[32:35], v[136:139], v[196:199], v[32:35]
	v_mfma_f32_16x16x32_bf16 v[24:27], v[128:131], v[204:207], v[24:27]
	v_mfma_f32_16x16x32_bf16 v[16:19], v[136:139], v[204:207], v[16:19]
	v_mfma_f32_16x16x32_bf16 v[60:63], v[132:135], v[184:187], v[60:63]
	v_mfma_f32_16x16x32_bf16 v[56:59], v[140:143], v[184:187], v[56:59]
	v_mfma_f32_16x16x32_bf16 v[52:55], v[132:135], v[192:195], v[52:55]
	v_mfma_f32_16x16x32_bf16 v[48:51], v[140:143], v[192:195], v[48:51]
	v_mfma_f32_16x16x32_bf16 v[40:43], v[132:135], v[200:203], v[40:43]
	v_mfma_f32_16x16x32_bf16 v[32:35], v[140:143], v[200:203], v[32:35]
	v_mfma_f32_16x16x32_bf16 v[24:27], v[132:135], v[212:215], v[24:27]
	v_mfma_f32_16x16x32_bf16 v[16:19], v[140:143], v[212:215], v[16:19]
	s_setprio 0
	s_setprio 1
	v_mfma_f32_16x16x32_bf16 v[44:47], v[144:147], v[180:183], v[44:47]
	v_mfma_f32_16x16x32_bf16 v[36:39], v[172:175], v[180:183], v[36:39]
	v_mfma_f32_16x16x32_bf16 v[28:31], v[144:147], v[188:191], v[28:31]
	v_mfma_f32_16x16x32_bf16 v[20:23], v[172:175], v[188:191], v[20:23]
	v_mfma_f32_16x16x32_bf16 v[12:15], v[144:147], v[196:199], v[12:15]
	v_mfma_f32_16x16x32_bf16 v[8:11], v[172:175], v[196:199], v[8:11]
	v_mfma_f32_16x16x32_bf16 v[4:7], v[144:147], v[204:207], v[4:7]
	v_mfma_f32_16x16x32_bf16 v[0:3], v[172:175], v[204:207], v[0:3]
	v_mfma_f32_16x16x32_bf16 v[44:47], v[148:151], v[184:187], v[44:47]
	v_mfma_f32_16x16x32_bf16 v[36:39], v[176:179], v[184:187], v[36:39]
	v_mfma_f32_16x16x32_bf16 v[28:31], v[148:151], v[192:195], v[28:31]
	v_mfma_f32_16x16x32_bf16 v[20:23], v[176:179], v[192:195], v[20:23]
	v_mfma_f32_16x16x32_bf16 v[12:15], v[148:151], v[200:203], v[12:15]
	v_mfma_f32_16x16x32_bf16 v[8:11], v[176:179], v[200:203], v[8:11]
	v_mfma_f32_16x16x32_bf16 v[4:7], v[148:151], v[212:215], v[4:7]
	v_mfma_f32_16x16x32_bf16 v[0:3], v[176:179], v[212:215], v[0:3]
	s_setprio 0
	s_barrier
	s_add_u32 s8, s8, 0x1000
	s_addc_u32 s9, s9, 0
	s_add_u32 s41, s41, 0x1000
	s_addc_u32 s46, s46, 0
	s_cmp_ge_i32 s55, s4
	s_mov_b32 s47, s55
	s_cbranch_scc0 .LBB0_917
	s_and_b64 vcc, exec, s[36:37]
	s_cbranch_vccz .LBB0_922
	s_barrier
	s_cmp_lt_i32 s12, 0
	s_mov_b64 s[8:9], -1
	s_cbranch_scc1 .LBB0_923
